# select passes: packed f32 fma in the head sums split back into single f32 fma/mul (packed VOP3P ops beside MFMAs stall); same arithmetic
# speedup vs baseline: 1.0166x; 1.0108x over previous
.Lp1_c1:
	ds_read_b128 v[176:179], v99 offset:8192
	ds_read_b128 v[180:183], v99 offset:12288
	ds_read_b128 v[230:233], v99 offset:9216
	ds_read_b128 v[234:237], v99 offset:13312
	ds_read_b128 v[238:241], v99 offset:10240
	ds_read_b128 v[242:245], v99 offset:14336
	ds_read_b128 v[246:249], v99 offset:11264
	ds_read_b128 v[50:53], v99 offset:15360
	v_max_i32_e32 v56, 0, v8
	v_max_i32_e32 v57, 0, v0
	v_max_i32_e32 v60, 0, v9
	v_max_i32_e32 v61, 0, v1
	v_max_i32_e32 v64, 0, v10
	v_max_i32_e32 v65, 0, v2
	v_max_i32_e32 v154, 0, v11
	v_max_i32_e32 v155, 0, v3
	v_mul_f32_e32 v156, v100, v56
	v_mul_f32_e32 v157, v101, v57
	s_waitcnt lgkmcnt(7)
	v_mfma_f32_32x32x16_bf16 v[198:213], v[34:37], v[176:179], 0
	v_fmac_f32_e32 v156, v102, v60
	v_fmac_f32_e32 v157, v103, v61
	v_fmac_f32_e32 v156, v104, v64
	v_fmac_f32_e32 v157, v105, v65
	v_fmac_f32_e32 v156, v106, v154
	v_fmac_f32_e32 v157, v107, v155
	v_max_i32_e32 v56, 0, v12
	v_max_i32_e32 v57, 0, v4
	v_max_i32_e32 v60, 0, v13
	v_max_i32_e32 v61, 0, v5
	v_max_i32_e32 v64, 0, v14
	s_waitcnt lgkmcnt(6)
	v_mfma_f32_32x32x16_bf16 v[214:229], v[34:37], v[180:183], 0
	s_waitcnt vmcnt(3)
	ds_write_b128 v140, v[20:23]
	s_add_i32 s1, s0, 5
	s_min_i32 s1, s1, s14
	v_mad_i64_i32 v[184:185], s[2:3], s1, v193, v[116:117]
	global_load_dwordx4 v[20:23], v[184:185], off
	v_max_i32_e32 v65, 0, v6
	v_max_i32_e32 v154, 0, v15
	v_max_i32_e32 v155, 0, v7
	v_fmac_f32_e32 v156, v108, v56
	v_fmac_f32_e32 v157, v109, v57
	v_fmac_f32_e32 v156, v110, v60
	v_fmac_f32_e32 v157, v111, v61
	v_fmac_f32_e32 v156, v112, v64
	v_fmac_f32_e32 v157, v113, v65
	v_fmac_f32_e32 v156, v114, v154
	v_fmac_f32_e32 v157, v115, v155
	s_waitcnt lgkmcnt(6)
	v_mfma_f32_32x32x16_bf16 v[198:213], v[38:41], v[230:233], v[198:213]
	v_bfe_u32 v56, v157, 19, 12
	v_bfe_u32 v64, v156, 19, 12
	v_med3_u32 v56, v56, s94, v194
	v_med3_u32 v64, v64, s94, v194
	v_sub_u32_e32 v57, 0x86f, v56
	v_add_u32_e32 v60, 0xfffffb90, v56
	v_sub_u32_e32 v65, 0x86f, v64
	v_add_u32_e32 v154, 0xfffffb90, v64
	v_cmp_gt_f32_e32 vcc, 0, v157
	s_nop 1
	v_cndmask_b32_e32 v56, v60, v57, vcc
	s_waitcnt lgkmcnt(5)
	v_mfma_f32_32x32x16_bf16 v[214:229], v[38:41], v[234:237], v[214:229]
	v_cmp_gt_f32_e32 vcc, 0, v156
	v_lshl_add_u32 v61, v56, 2, v33
	ds_add_u32 v61, v188
	v_cndmask_b32_e32 v64, v154, v65, vcc
	v_lshl_add_u32 v155, v64, 2, v33
	ds_add_u32 v155, v188 offset:4096
	v_max_i32_e32 v56, 0, v168
	v_max_i32_e32 v57, 0, v160
	v_max_i32_e32 v60, 0, v169
	v_max_i32_e32 v61, 0, v161
	v_max_i32_e32 v64, 0, v170
	s_waitcnt lgkmcnt(6)
	v_mfma_f32_32x32x16_bf16 v[198:213], v[42:45], v[238:241], v[198:213]
	v_max_i32_e32 v65, 0, v162
	v_max_i32_e32 v154, 0, v171
	v_max_i32_e32 v155, 0, v163
	v_mul_f32_e32 v156, v100, v56
	v_mul_f32_e32 v157, v101, v57
	v_fmac_f32_e32 v156, v102, v60
	v_fmac_f32_e32 v157, v103, v61
	v_fmac_f32_e32 v156, v104, v64
	v_fmac_f32_e32 v157, v105, v65
	v_fmac_f32_e32 v156, v106, v154
	v_fmac_f32_e32 v157, v107, v155
	s_waitcnt lgkmcnt(5)
	v_mfma_f32_32x32x16_bf16 v[214:229], v[42:45], v[242:245], v[214:229]
	v_max_i32_e32 v56, 0, v172
	v_max_i32_e32 v57, 0, v164
	v_max_i32_e32 v60, 0, v173
	v_max_i32_e32 v61, 0, v165
	v_max_i32_e32 v64, 0, v174
	v_max_i32_e32 v65, 0, v166
	v_max_i32_e32 v154, 0, v175
	v_max_i32_e32 v155, 0, v167
	v_fmac_f32_e32 v156, v108, v56
	v_fmac_f32_e32 v157, v109, v57
	v_fmac_f32_e32 v156, v110, v60
	s_waitcnt lgkmcnt(4)
	v_mfma_f32_32x32x16_bf16 v[198:213], v[46:49], v[246:249], v[198:213]
	v_fmac_f32_e32 v157, v111, v61
	v_fmac_f32_e32 v156, v112, v64
	v_fmac_f32_e32 v157, v113, v65
	v_fmac_f32_e32 v156, v114, v154
	v_fmac_f32_e32 v157, v115, v155
	v_bfe_u32 v56, v157, 19, 12
	v_bfe_u32 v64, v156, 19, 12
	v_med3_u32 v56, v56, s94, v194
	v_med3_u32 v64, v64, s94, v194
	v_sub_u32_e32 v57, 0x86f, v56
	v_add_u32_e32 v60, 0xfffffb90, v56
	s_waitcnt lgkmcnt(3)
	v_mfma_f32_32x32x16_bf16 v[214:229], v[46:49], v[50:53], v[214:229]
	v_sub_u32_e32 v65, 0x86f, v64
	v_add_u32_e32 v154, 0xfffffb90, v64
	v_cmp_gt_f32_e32 vcc, 0, v157
	s_nop 1
	v_cndmask_b32_e32 v56, v60, v57, vcc
	v_cmp_gt_f32_e32 vcc, 0, v156
	v_lshl_add_u32 v61, v56, 2, v33
	ds_add_u32 v61, v188
	v_cndmask_b32_e32 v64, v154, v65, vcc
	v_lshl_add_u32 v155, v64, 2, v33
	ds_add_u32 v155, v188 offset:4096
	s_waitcnt lgkmcnt(0)
	s_barrier
	s_add_u32 s0, s0, 1
	s_cmp_ge_u32 s0, s13
	s_cbranch_scc1 .Lp1_drain1
.Lp1_c2:
	ds_read_b128 v[176:179], v99 offset:0
	ds_read_b128 v[180:183], v99 offset:4096
	ds_read_b128 v[230:233], v99 offset:1024
	ds_read_b128 v[234:237], v99 offset:5120
	ds_read_b128 v[238:241], v99 offset:2048
	ds_read_b128 v[242:245], v99 offset:6144
	ds_read_b128 v[246:249], v99 offset:3072
	ds_read_b128 v[50:53], v99 offset:7168
	v_max_i32_e32 v56, 0, v206
	v_max_i32_e32 v57, 0, v198
	v_max_i32_e32 v60, 0, v207
	v_max_i32_e32 v61, 0, v199
	v_max_i32_e32 v64, 0, v208
	v_max_i32_e32 v65, 0, v200
	v_max_i32_e32 v154, 0, v209
	v_max_i32_e32 v155, 0, v201
	v_mul_f32_e32 v156, v100, v56
	v_mul_f32_e32 v157, v101, v57
	s_waitcnt lgkmcnt(7)
	v_mfma_f32_32x32x16_bf16 v[0:15], v[34:37], v[176:179], 0
	v_fmac_f32_e32 v156, v102, v60
	v_fmac_f32_e32 v157, v103, v61
	v_fmac_f32_e32 v156, v104, v64
	v_fmac_f32_e32 v157, v105, v65
	v_fmac_f32_e32 v156, v106, v154
	v_fmac_f32_e32 v157, v107, v155
	v_max_i32_e32 v56, 0, v210
	v_max_i32_e32 v57, 0, v202
	v_max_i32_e32 v60, 0, v211
	v_max_i32_e32 v61, 0, v203
	v_max_i32_e32 v64, 0, v212
	s_waitcnt lgkmcnt(6)
	v_mfma_f32_32x32x16_bf16 v[160:175], v[34:37], v[180:183], 0
	s_waitcnt vmcnt(3)
	ds_write_b128 v140, v[24:27] offset:8192
	s_add_i32 s1, s0, 5
	s_min_i32 s1, s1, s14
	v_mad_i64_i32 v[184:185], s[2:3], s1, v193, v[116:117]
	global_load_dwordx4 v[24:27], v[184:185], off
	v_max_i32_e32 v65, 0, v204
	v_max_i32_e32 v154, 0, v213
	v_max_i32_e32 v155, 0, v205
	v_fmac_f32_e32 v156, v108, v56
	v_fmac_f32_e32 v157, v109, v57
	v_fmac_f32_e32 v156, v110, v60
	v_fmac_f32_e32 v157, v111, v61
	v_fmac_f32_e32 v156, v112, v64
	v_fmac_f32_e32 v157, v113, v65
	v_fmac_f32_e32 v156, v114, v154
	v_fmac_f32_e32 v157, v115, v155
	s_waitcnt lgkmcnt(6)
	v_mfma_f32_32x32x16_bf16 v[0:15], v[38:41], v[230:233], v[0:15]
	v_bfe_u32 v56, v157, 19, 12
	v_bfe_u32 v64, v156, 19, 12
	v_med3_u32 v56, v56, s94, v194
	v_med3_u32 v64, v64, s94, v194
	v_sub_u32_e32 v57, 0x86f, v56
	v_add_u32_e32 v60, 0xfffffb90, v56
	v_sub_u32_e32 v65, 0x86f, v64
	v_add_u32_e32 v154, 0xfffffb90, v64
	v_cmp_gt_f32_e32 vcc, 0, v157
	s_nop 1
	v_cndmask_b32_e32 v56, v60, v57, vcc
	s_waitcnt lgkmcnt(5)
	v_mfma_f32_32x32x16_bf16 v[160:175], v[38:41], v[234:237], v[160:175]
	v_cmp_gt_f32_e32 vcc, 0, v156
	v_lshl_add_u32 v61, v56, 2, v33
	ds_add_u32 v61, v188
	v_cndmask_b32_e32 v64, v154, v65, vcc
	v_lshl_add_u32 v155, v64, 2, v33
	ds_add_u32 v155, v188 offset:4096
	v_max_i32_e32 v56, 0, v222
	v_max_i32_e32 v57, 0, v214
	v_max_i32_e32 v60, 0, v223
	v_max_i32_e32 v61, 0, v215
	v_max_i32_e32 v64, 0, v224
	s_waitcnt lgkmcnt(6)
	v_mfma_f32_32x32x16_bf16 v[0:15], v[42:45], v[238:241], v[0:15]
	v_max_i32_e32 v65, 0, v216
	v_max_i32_e32 v154, 0, v225
	v_max_i32_e32 v155, 0, v217
	v_mul_f32_e32 v156, v100, v56
	v_mul_f32_e32 v157, v101, v57
	v_fmac_f32_e32 v156, v102, v60
	v_fmac_f32_e32 v157, v103, v61
	v_fmac_f32_e32 v156, v104, v64
	v_fmac_f32_e32 v157, v105, v65
	v_fmac_f32_e32 v156, v106, v154
	v_fmac_f32_e32 v157, v107, v155
	s_waitcnt lgkmcnt(5)
	v_mfma_f32_32x32x16_bf16 v[160:175], v[42:45], v[242:245], v[160:175]
	v_max_i32_e32 v56, 0, v226
	v_max_i32_e32 v57, 0, v218
	v_max_i32_e32 v60, 0, v227
	v_max_i32_e32 v61, 0, v219
	v_max_i32_e32 v64, 0, v228
	v_max_i32_e32 v65, 0, v220
	v_max_i32_e32 v154, 0, v229
	v_max_i32_e32 v155, 0, v221
	v_fmac_f32_e32 v156, v108, v56
	v_fmac_f32_e32 v157, v109, v57
	v_fmac_f32_e32 v156, v110, v60
	s_waitcnt lgkmcnt(4)
	v_mfma_f32_32x32x16_bf16 v[0:15], v[46:49], v[246:249], v[0:15]
	v_fmac_f32_e32 v157, v111, v61
	v_fmac_f32_e32 v156, v112, v64
	v_fmac_f32_e32 v157, v113, v65
	v_fmac_f32_e32 v156, v114, v154
	v_fmac_f32_e32 v157, v115, v155
	v_bfe_u32 v56, v157, 19, 12
	v_bfe_u32 v64, v156, 19, 12
	v_med3_u32 v56, v56, s94, v194
	v_med3_u32 v64, v64, s94, v194
	v_sub_u32_e32 v57, 0x86f, v56
	v_add_u32_e32 v60, 0xfffffb90, v56
	s_waitcnt lgkmcnt(3)
	v_mfma_f32_32x32x16_bf16 v[160:175], v[46:49], v[50:53], v[160:175]
	v_sub_u32_e32 v65, 0x86f, v64
	v_add_u32_e32 v154, 0xfffffb90, v64
	v_cmp_gt_f32_e32 vcc, 0, v157
	s_nop 1
	v_cndmask_b32_e32 v56, v60, v57, vcc
	v_cmp_gt_f32_e32 vcc, 0, v156
	v_lshl_add_u32 v61, v56, 2, v33
	ds_add_u32 v61, v188
	v_cndmask_b32_e32 v64, v154, v65, vcc
	v_lshl_add_u32 v155, v64, 2, v33
	ds_add_u32 v155, v188 offset:4096
	s_waitcnt lgkmcnt(0)
	s_barrier
	s_add_u32 s0, s0, 1
	s_cmp_ge_u32 s0, s13
	s_cbranch_scc1 .Lp1_drain0
.Lp1_c3:
	ds_read_b128 v[176:179], v99 offset:8192
	ds_read_b128 v[180:183], v99 offset:12288
	ds_read_b128 v[230:233], v99 offset:9216
	ds_read_b128 v[234:237], v99 offset:13312
	ds_read_b128 v[238:241], v99 offset:10240
	ds_read_b128 v[242:245], v99 offset:14336
	ds_read_b128 v[246:249], v99 offset:11264
	ds_read_b128 v[50:53], v99 offset:15360
	v_max_i32_e32 v56, 0, v8
	v_max_i32_e32 v57, 0, v0
	v_max_i32_e32 v60, 0, v9
	v_max_i32_e32 v61, 0, v1
	v_max_i32_e32 v64, 0, v10
	v_max_i32_e32 v65, 0, v2
	v_max_i32_e32 v154, 0, v11
	v_max_i32_e32 v155, 0, v3
	v_mul_f32_e32 v156, v100, v56
	v_mul_f32_e32 v157, v101, v57
	s_waitcnt lgkmcnt(7)
	v_mfma_f32_32x32x16_bf16 v[198:213], v[34:37], v[176:179], 0
	v_fmac_f32_e32 v156, v102, v60
	v_fmac_f32_e32 v157, v103, v61
	v_fmac_f32_e32 v156, v104, v64
	v_fmac_f32_e32 v157, v105, v65
	v_fmac_f32_e32 v156, v106, v154
	v_fmac_f32_e32 v157, v107, v155
	v_max_i32_e32 v56, 0, v12
	v_max_i32_e32 v57, 0, v4
	v_max_i32_e32 v60, 0, v13
	v_max_i32_e32 v61, 0, v5
	v_max_i32_e32 v64, 0, v14
	s_waitcnt lgkmcnt(6)
	v_mfma_f32_32x32x16_bf16 v[214:229], v[34:37], v[180:183], 0
	s_waitcnt vmcnt(3)
	ds_write_b128 v140, v[28:31]
	s_add_i32 s1, s0, 5
	s_min_i32 s1, s1, s14
	v_mad_i64_i32 v[184:185], s[2:3], s1, v193, v[116:117]
	global_load_dwordx4 v[28:31], v[184:185], off
	v_max_i32_e32 v65, 0, v6
	v_max_i32_e32 v154, 0, v15
	v_max_i32_e32 v155, 0, v7
	v_fmac_f32_e32 v156, v108, v56
	v_fmac_f32_e32 v157, v109, v57
	v_fmac_f32_e32 v156, v110, v60
	v_fmac_f32_e32 v157, v111, v61
	v_fmac_f32_e32 v156, v112, v64
	v_fmac_f32_e32 v157, v113, v65
	v_fmac_f32_e32 v156, v114, v154
	v_fmac_f32_e32 v157, v115, v155
	s_waitcnt lgkmcnt(6)
	v_mfma_f32_32x32x16_bf16 v[198:213], v[38:41], v[230:233], v[198:213]
	v_bfe_u32 v56, v157, 19, 12
	v_bfe_u32 v64, v156, 19, 12
	v_med3_u32 v56, v56, s94, v194
	v_med3_u32 v64, v64, s94, v194
	v_sub_u32_e32 v57, 0x86f, v56
	v_add_u32_e32 v60, 0xfffffb90, v56
	v_sub_u32_e32 v65, 0x86f, v64
	v_add_u32_e32 v154, 0xfffffb90, v64
	v_cmp_gt_f32_e32 vcc, 0, v157
	s_nop 1
	v_cndmask_b32_e32 v56, v60, v57, vcc
	s_waitcnt lgkmcnt(5)
	v_mfma_f32_32x32x16_bf16 v[214:229], v[38:41], v[234:237], v[214:229]
	v_cmp_gt_f32_e32 vcc, 0, v156
	v_lshl_add_u32 v61, v56, 2, v33
	ds_add_u32 v61, v188
	v_cndmask_b32_e32 v64, v154, v65, vcc
	v_lshl_add_u32 v155, v64, 2, v33
	ds_add_u32 v155, v188 offset:4096
	v_max_i32_e32 v56, 0, v168
	v_max_i32_e32 v57, 0, v160
	v_max_i32_e32 v60, 0, v169
	v_max_i32_e32 v61, 0, v161
	v_max_i32_e32 v64, 0, v170
	s_waitcnt lgkmcnt(6)
	v_mfma_f32_32x32x16_bf16 v[198:213], v[42:45], v[238:241], v[198:213]
	v_max_i32_e32 v65, 0, v162
	v_max_i32_e32 v154, 0, v171
	v_max_i32_e32 v155, 0, v163
	v_mul_f32_e32 v156, v100, v56
	v_mul_f32_e32 v157, v101, v57
	v_fmac_f32_e32 v156, v102, v60
	v_fmac_f32_e32 v157, v103, v61
	v_fmac_f32_e32 v156, v104, v64
	v_fmac_f32_e32 v157, v105, v65
	v_fmac_f32_e32 v156, v106, v154
	v_fmac_f32_e32 v157, v107, v155
	s_waitcnt lgkmcnt(5)
	v_mfma_f32_32x32x16_bf16 v[214:229], v[42:45], v[242:245], v[214:229]
	v_max_i32_e32 v56, 0, v172
	v_max_i32_e32 v57, 0, v164
	v_max_i32_e32 v60, 0, v173
	v_max_i32_e32 v61, 0, v165
	v_max_i32_e32 v64, 0, v174
	v_max_i32_e32 v65, 0, v166
	v_max_i32_e32 v154, 0, v175
	v_max_i32_e32 v155, 0, v167
	v_fmac_f32_e32 v156, v108, v56
	v_fmac_f32_e32 v157, v109, v57
	v_fmac_f32_e32 v156, v110, v60
	s_waitcnt lgkmcnt(4)
	v_mfma_f32_32x32x16_bf16 v[198:213], v[46:49], v[246:249], v[198:213]
	v_fmac_f32_e32 v157, v111, v61
	v_fmac_f32_e32 v156, v112, v64
	v_fmac_f32_e32 v157, v113, v65
	v_fmac_f32_e32 v156, v114, v154
	v_fmac_f32_e32 v157, v115, v155
	v_bfe_u32 v56, v157, 19, 12
	v_bfe_u32 v64, v156, 19, 12
	v_med3_u32 v56, v56, s94, v194
	v_med3_u32 v64, v64, s94, v194
	v_sub_u32_e32 v57, 0x86f, v56
	v_add_u32_e32 v60, 0xfffffb90, v56
	s_waitcnt lgkmcnt(3)
	v_mfma_f32_32x32x16_bf16 v[214:229], v[46:49], v[50:53], v[214:229]
	v_sub_u32_e32 v65, 0x86f, v64
	v_add_u32_e32 v154, 0xfffffb90, v64
	v_cmp_gt_f32_e32 vcc, 0, v157
	s_nop 1
	v_cndmask_b32_e32 v56, v60, v57, vcc
	v_cmp_gt_f32_e32 vcc, 0, v156
	v_lshl_add_u32 v61, v56, 2, v33
	ds_add_u32 v61, v188
	v_cndmask_b32_e32 v64, v154, v65, vcc
	v_lshl_add_u32 v155, v64, 2, v33
	ds_add_u32 v155, v188 offset:4096
	s_waitcnt lgkmcnt(0)
	s_barrier
	s_add_u32 s0, s0, 1
	s_cmp_ge_u32 s0, s13
	s_cbranch_scc1 .Lp1_drain1
.Lp1_c0:
	ds_read_b128 v[176:179], v99 offset:0
	ds_read_b128 v[180:183], v99 offset:4096
	ds_read_b128 v[230:233], v99 offset:1024
	ds_read_b128 v[234:237], v99 offset:5120
	ds_read_b128 v[238:241], v99 offset:2048
	ds_read_b128 v[242:245], v99 offset:6144
	ds_read_b128 v[246:249], v99 offset:3072
	ds_read_b128 v[50:53], v99 offset:7168
	v_max_i32_e32 v56, 0, v206
	v_max_i32_e32 v57, 0, v198
	v_max_i32_e32 v60, 0, v207
	v_max_i32_e32 v61, 0, v199
	v_max_i32_e32 v64, 0, v208
	v_max_i32_e32 v65, 0, v200
	v_max_i32_e32 v154, 0, v209
	v_max_i32_e32 v155, 0, v201
	v_mul_f32_e32 v156, v100, v56
	v_mul_f32_e32 v157, v101, v57
	s_waitcnt lgkmcnt(7)
	v_mfma_f32_32x32x16_bf16 v[0:15], v[34:37], v[176:179], 0
	v_fmac_f32_e32 v156, v102, v60
	v_fmac_f32_e32 v157, v103, v61
	v_fmac_f32_e32 v156, v104, v64
	v_fmac_f32_e32 v157, v105, v65
	v_fmac_f32_e32 v156, v106, v154
	v_fmac_f32_e32 v157, v107, v155
	v_max_i32_e32 v56, 0, v210
	v_max_i32_e32 v57, 0, v202
	v_max_i32_e32 v60, 0, v211
	v_max_i32_e32 v61, 0, v203
	v_max_i32_e32 v64, 0, v212
	s_waitcnt lgkmcnt(6)
	v_mfma_f32_32x32x16_bf16 v[160:175], v[34:37], v[180:183], 0
	s_waitcnt vmcnt(3)
	ds_write_b128 v140, v[16:19] offset:8192
	s_add_i32 s1, s0, 5
	s_min_i32 s1, s1, s14
	v_mad_i64_i32 v[184:185], s[2:3], s1, v193, v[116:117]
	global_load_dwordx4 v[16:19], v[184:185], off
	v_max_i32_e32 v65, 0, v204
	v_max_i32_e32 v154, 0, v213
	v_max_i32_e32 v155, 0, v205
	v_fmac_f32_e32 v156, v108, v56
	v_fmac_f32_e32 v157, v109, v57
	v_fmac_f32_e32 v156, v110, v60
	v_fmac_f32_e32 v157, v111, v61
	v_fmac_f32_e32 v156, v112, v64
	v_fmac_f32_e32 v157, v113, v65
	v_fmac_f32_e32 v156, v114, v154
	v_fmac_f32_e32 v157, v115, v155
	s_waitcnt lgkmcnt(6)
	v_mfma_f32_32x32x16_bf16 v[0:15], v[38:41], v[230:233], v[0:15]
	v_bfe_u32 v56, v157, 19, 12
	v_bfe_u32 v64, v156, 19, 12
	v_med3_u32 v56, v56, s94, v194
	v_med3_u32 v64, v64, s94, v194
	v_sub_u32_e32 v57, 0x86f, v56
	v_add_u32_e32 v60, 0xfffffb90, v56
	v_sub_u32_e32 v65, 0x86f, v64
	v_add_u32_e32 v154, 0xfffffb90, v64
	v_cmp_gt_f32_e32 vcc, 0, v157
	s_nop 1
	v_cndmask_b32_e32 v56, v60, v57, vcc
	s_waitcnt lgkmcnt(5)
	v_mfma_f32_32x32x16_bf16 v[160:175], v[38:41], v[234:237], v[160:175]
	v_cmp_gt_f32_e32 vcc, 0, v156
	v_lshl_add_u32 v61, v56, 2, v33
	ds_add_u32 v61, v188
	v_cndmask_b32_e32 v64, v154, v65, vcc
	v_lshl_add_u32 v155, v64, 2, v33
	ds_add_u32 v155, v188 offset:4096
	v_max_i32_e32 v56, 0, v222
	v_max_i32_e32 v57, 0, v214
	v_max_i32_e32 v60, 0, v223
	v_max_i32_e32 v61, 0, v215
	v_max_i32_e32 v64, 0, v224
	s_waitcnt lgkmcnt(6)
	v_mfma_f32_32x32x16_bf16 v[0:15], v[42:45], v[238:241], v[0:15]
	v_max_i32_e32 v65, 0, v216
	v_max_i32_e32 v154, 0, v225
	v_max_i32_e32 v155, 0, v217
	v_mul_f32_e32 v156, v100, v56
	v_mul_f32_e32 v157, v101, v57
	v_fmac_f32_e32 v156, v102, v60
	v_fmac_f32_e32 v157, v103, v61
	v_fmac_f32_e32 v156, v104, v64
	v_fmac_f32_e32 v157, v105, v65
	v_fmac_f32_e32 v156, v106, v154
	v_fmac_f32_e32 v157, v107, v155
	s_waitcnt lgkmcnt(5)
	v_mfma_f32_32x32x16_bf16 v[160:175], v[42:45], v[242:245], v[160:175]
	v_max_i32_e32 v56, 0, v226
	v_max_i32_e32 v57, 0, v218
	v_max_i32_e32 v60, 0, v227
	v_max_i32_e32 v61, 0, v219
	v_max_i32_e32 v64, 0, v228
	v_max_i32_e32 v65, 0, v220
	v_max_i32_e32 v154, 0, v229
	v_max_i32_e32 v155, 0, v221
	v_fmac_f32_e32 v156, v108, v56
	v_fmac_f32_e32 v157, v109, v57
	v_fmac_f32_e32 v156, v110, v60
	s_waitcnt lgkmcnt(4)
	v_mfma_f32_32x32x16_bf16 v[0:15], v[46:49], v[246:249], v[0:15]
	v_fmac_f32_e32 v157, v111, v61
	v_fmac_f32_e32 v156, v112, v64
	v_fmac_f32_e32 v157, v113, v65
	v_fmac_f32_e32 v156, v114, v154
	v_fmac_f32_e32 v157, v115, v155
	v_bfe_u32 v56, v157, 19, 12
	v_bfe_u32 v64, v156, 19, 12
	v_med3_u32 v56, v56, s94, v194
	v_med3_u32 v64, v64, s94, v194
	v_sub_u32_e32 v57, 0x86f, v56
	v_add_u32_e32 v60, 0xfffffb90, v56
	s_waitcnt lgkmcnt(3)
	v_mfma_f32_32x32x16_bf16 v[160:175], v[46:49], v[50:53], v[160:175]
	v_sub_u32_e32 v65, 0x86f, v64
	v_add_u32_e32 v154, 0xfffffb90, v64
	v_cmp_gt_f32_e32 vcc, 0, v157
	s_nop 1
	v_cndmask_b32_e32 v56, v60, v57, vcc
	v_cmp_gt_f32_e32 vcc, 0, v156
	v_lshl_add_u32 v61, v56, 2, v33
	ds_add_u32 v61, v188
	v_cndmask_b32_e32 v64, v154, v65, vcc
	v_lshl_add_u32 v155, v64, 2, v33
	ds_add_u32 v155, v188 offset:4096
	s_waitcnt lgkmcnt(0)
	s_barrier
	s_add_u32 s0, s0, 1
	s_cmp_ge_u32 s0, s13
	s_cbranch_scc1 .Lp1_drain0
	s_branch .Lp1_c1
.Lp1_drain0:
	v_max_i32_e32 v56, 0, v8
	v_max_i32_e32 v57, 0, v0
	v_max_i32_e32 v60, 0, v9
	v_max_i32_e32 v61, 0, v1
	v_max_i32_e32 v64, 0, v10
	v_max_i32_e32 v65, 0, v2
	v_max_i32_e32 v154, 0, v11
	v_max_i32_e32 v155, 0, v3
	v_mul_f32_e32 v156, v100, v56
	v_mul_f32_e32 v157, v101, v57
	v_fmac_f32_e32 v156, v102, v60
	v_fmac_f32_e32 v157, v103, v61
	v_fmac_f32_e32 v156, v104, v64
	v_fmac_f32_e32 v157, v105, v65
	v_fmac_f32_e32 v156, v106, v154
	v_fmac_f32_e32 v157, v107, v155
	v_max_i32_e32 v56, 0, v12
	v_max_i32_e32 v57, 0, v4
	v_max_i32_e32 v60, 0, v13
	v_max_i32_e32 v61, 0, v5
	v_max_i32_e32 v64, 0, v14
	v_max_i32_e32 v65, 0, v6
	v_max_i32_e32 v154, 0, v15
	v_max_i32_e32 v155, 0, v7
	v_fmac_f32_e32 v156, v108, v56
	v_fmac_f32_e32 v157, v109, v57
	v_fmac_f32_e32 v156, v110, v60
	v_fmac_f32_e32 v157, v111, v61
	v_fmac_f32_e32 v156, v112, v64
	v_fmac_f32_e32 v157, v113, v65
	v_fmac_f32_e32 v156, v114, v154
	v_fmac_f32_e32 v157, v115, v155
	v_bfe_u32 v56, v157, 19, 12
	v_bfe_u32 v64, v156, 19, 12
	v_med3_u32 v56, v56, s94, v194
	v_med3_u32 v64, v64, s94, v194
	v_sub_u32_e32 v57, 0x86f, v56
	v_add_u32_e32 v60, 0xfffffb90, v56
	v_sub_u32_e32 v65, 0x86f, v64
	v_add_u32_e32 v154, 0xfffffb90, v64
	v_cmp_gt_f32_e32 vcc, 0, v157
	s_nop 1
	v_cndmask_b32_e32 v56, v60, v57, vcc
	v_cmp_gt_f32_e32 vcc, 0, v156
	v_lshl_add_u32 v61, v56, 2, v33
	ds_add_u32 v61, v188
	v_cndmask_b32_e32 v64, v154, v65, vcc
	v_lshl_add_u32 v155, v64, 2, v33
	ds_add_u32 v155, v188 offset:4096
	v_max_i32_e32 v56, 0, v168
	v_max_i32_e32 v57, 0, v160
	v_max_i32_e32 v60, 0, v169
	v_max_i32_e32 v61, 0, v161
	v_max_i32_e32 v64, 0, v170
	v_max_i32_e32 v65, 0, v162
	v_max_i32_e32 v154, 0, v171
	v_max_i32_e32 v155, 0, v163
	v_mul_f32_e32 v156, v100, v56
	v_mul_f32_e32 v157, v101, v57
	v_fmac_f32_e32 v156, v102, v60
	v_fmac_f32_e32 v157, v103, v61
	v_fmac_f32_e32 v156, v104, v64
	v_fmac_f32_e32 v157, v105, v65
	v_fmac_f32_e32 v156, v106, v154
	v_fmac_f32_e32 v157, v107, v155
	v_max_i32_e32 v56, 0, v172
	v_max_i32_e32 v57, 0, v164
	v_max_i32_e32 v60, 0, v173
	v_max_i32_e32 v61, 0, v165
	v_max_i32_e32 v64, 0, v174
	v_max_i32_e32 v65, 0, v166
	v_max_i32_e32 v154, 0, v175
	v_max_i32_e32 v155, 0, v167
	v_fmac_f32_e32 v156, v108, v56
	v_fmac_f32_e32 v157, v109, v57
	v_fmac_f32_e32 v156, v110, v60
	v_fmac_f32_e32 v157, v111, v61
	v_fmac_f32_e32 v156, v112, v64
	v_fmac_f32_e32 v157, v113, v65
	v_fmac_f32_e32 v156, v114, v154
	v_fmac_f32_e32 v157, v115, v155
	v_bfe_u32 v56, v157, 19, 12
	v_bfe_u32 v64, v156, 19, 12
	v_med3_u32 v56, v56, s94, v194
	v_med3_u32 v64, v64, s94, v194
	v_sub_u32_e32 v57, 0x86f, v56
	v_add_u32_e32 v60, 0xfffffb90, v56
	v_sub_u32_e32 v65, 0x86f, v64
	v_add_u32_e32 v154, 0xfffffb90, v64
	v_cmp_gt_f32_e32 vcc, 0, v157
	s_nop 1
	v_cndmask_b32_e32 v56, v60, v57, vcc
	v_cmp_gt_f32_e32 vcc, 0, v156
	v_lshl_add_u32 v61, v56, 2, v33
	ds_add_u32 v61, v188
	v_cndmask_b32_e32 v64, v154, v65, vcc
	v_lshl_add_u32 v155, v64, 2, v33
	ds_add_u32 v155, v188 offset:4096
	s_branch .LBB0_904
.Lp1_drain1:
	v_max_i32_e32 v56, 0, v206
	v_max_i32_e32 v57, 0, v198
	v_max_i32_e32 v60, 0, v207
	v_max_i32_e32 v61, 0, v199
	v_max_i32_e32 v64, 0, v208
	v_max_i32_e32 v65, 0, v200
	v_max_i32_e32 v154, 0, v209
	v_max_i32_e32 v155, 0, v201
	v_mul_f32_e32 v156, v100, v56
	v_mul_f32_e32 v157, v101, v57
	v_fmac_f32_e32 v156, v102, v60
	v_fmac_f32_e32 v157, v103, v61
	v_fmac_f32_e32 v156, v104, v64
	v_fmac_f32_e32 v157, v105, v65
	v_fmac_f32_e32 v156, v106, v154
	v_fmac_f32_e32 v157, v107, v155
	v_max_i32_e32 v56, 0, v210
	v_max_i32_e32 v57, 0, v202
	v_max_i32_e32 v60, 0, v211
	v_max_i32_e32 v61, 0, v203
	v_max_i32_e32 v64, 0, v212
	v_max_i32_e32 v65, 0, v204
	v_max_i32_e32 v154, 0, v213
	v_max_i32_e32 v155, 0, v205
	v_fmac_f32_e32 v156, v108, v56
	v_fmac_f32_e32 v157, v109, v57
	v_fmac_f32_e32 v156, v110, v60
	v_fmac_f32_e32 v157, v111, v61
	v_fmac_f32_e32 v156, v112, v64
	v_fmac_f32_e32 v157, v113, v65
	v_fmac_f32_e32 v156, v114, v154
	v_fmac_f32_e32 v157, v115, v155
	v_bfe_u32 v56, v157, 19, 12
	v_bfe_u32 v64, v156, 19, 12
	v_med3_u32 v56, v56, s94, v194
	v_med3_u32 v64, v64, s94, v194
	v_sub_u32_e32 v57, 0x86f, v56
	v_add_u32_e32 v60, 0xfffffb90, v56
	v_sub_u32_e32 v65, 0x86f, v64
	v_add_u32_e32 v154, 0xfffffb90, v64
	v_cmp_gt_f32_e32 vcc, 0, v157
	s_nop 1
	v_cndmask_b32_e32 v56, v60, v57, vcc
	v_cmp_gt_f32_e32 vcc, 0, v156
	v_lshl_add_u32 v61, v56, 2, v33
	ds_add_u32 v61, v188
	v_cndmask_b32_e32 v64, v154, v65, vcc
	v_lshl_add_u32 v155, v64, 2, v33
	ds_add_u32 v155, v188 offset:4096
	v_max_i32_e32 v56, 0, v222
	v_max_i32_e32 v57, 0, v214
	v_max_i32_e32 v60, 0, v223
	v_max_i32_e32 v61, 0, v215
	v_max_i32_e32 v64, 0, v224
	v_max_i32_e32 v65, 0, v216
	v_max_i32_e32 v154, 0, v225
	v_max_i32_e32 v155, 0, v217
	v_mul_f32_e32 v156, v100, v56
	v_mul_f32_e32 v157, v101, v57
	v_fmac_f32_e32 v156, v102, v60
	v_fmac_f32_e32 v157, v103, v61
	v_fmac_f32_e32 v156, v104, v64
	v_fmac_f32_e32 v157, v105, v65
	v_fmac_f32_e32 v156, v106, v154
	v_fmac_f32_e32 v157, v107, v155
	v_max_i32_e32 v56, 0, v226
	v_max_i32_e32 v57, 0, v218
	v_max_i32_e32 v60, 0, v227
	v_max_i32_e32 v61, 0, v219
	v_max_i32_e32 v64, 0, v228
	v_max_i32_e32 v65, 0, v220
	v_max_i32_e32 v154, 0, v229
	v_max_i32_e32 v155, 0, v221
	v_fmac_f32_e32 v156, v108, v56
	v_fmac_f32_e32 v157, v109, v57
	v_fmac_f32_e32 v156, v110, v60
	v_fmac_f32_e32 v157, v111, v61
	v_fmac_f32_e32 v156, v112, v64
	v_fmac_f32_e32 v157, v113, v65
	v_fmac_f32_e32 v156, v114, v154
	v_fmac_f32_e32 v157, v115, v155
	v_bfe_u32 v56, v157, 19, 12
	v_bfe_u32 v64, v156, 19, 12
	v_med3_u32 v56, v56, s94, v194
	v_med3_u32 v64, v64, s94, v194
	v_sub_u32_e32 v57, 0x86f, v56
	v_add_u32_e32 v60, 0xfffffb90, v56
	v_sub_u32_e32 v65, 0x86f, v64
	v_add_u32_e32 v154, 0xfffffb90, v64
	v_cmp_gt_f32_e32 vcc, 0, v157
	s_nop 1
	v_cndmask_b32_e32 v56, v60, v57, vcc
	v_cmp_gt_f32_e32 vcc, 0, v156
	v_lshl_add_u32 v61, v56, 2, v33
	ds_add_u32 v61, v188
	v_cndmask_b32_e32 v64, v154, v65, vcc
	v_lshl_add_u32 v155, v64, 2, v33
	ds_add_u32 v155, v188 offset:4096
	s_branch .LBB0_904

.Lp2_c1:
	ds_read_b128 v[164:167], v99 offset:8192
	ds_read_b128 v[168:171], v99 offset:12288
	ds_read_b128 v[172:175], v99 offset:9216
	ds_read_b128 v[176:179], v99 offset:13312
	ds_read_b128 v[230:233], v99 offset:10240
	ds_read_b128 v[234:237], v99 offset:14336
	ds_read_b128 v[238:241], v99 offset:11264
	ds_read_b128 v[242:245], v99 offset:15360
	v_max_i32_e32 v246, 0, v24
	v_max_i32_e32 v247, 0, v16
	v_max_i32_e32 v248, 0, v25
	v_max_i32_e32 v249, 0, v17
	s_waitcnt lgkmcnt(7)
	v_mfma_f32_32x32x16_bf16 v[198:213], v[34:37], v[164:167], 0
	v_mul_f32_e32 v184, v100, v246
	v_mul_f32_e32 v185, v101, v247
	v_fmac_f32_e32 v184, v102, v248
	v_fmac_f32_e32 v185, v103, v249
	v_max_i32_e32 v246, 0, v26
	v_max_i32_e32 v247, 0, v18
	v_max_i32_e32 v248, 0, v27
	v_max_i32_e32 v249, 0, v19
	v_fmac_f32_e32 v184, v104, v246
	v_fmac_f32_e32 v185, v105, v247
	s_waitcnt lgkmcnt(6)
	v_mfma_f32_32x32x16_bf16 v[214:229], v[34:37], v[168:171], 0
	s_waitcnt vmcnt(3)
	ds_write_b128 v140, v[54:57]
	s_add_i32 s4, s18, 5
	s_min_i32 s4, s4, s14
	v_mad_i64_i32 v[164:165], s[4:5], s4, v193, v[116:117]
	global_load_dwordx4 v[54:57], v[164:165], off
	v_fmac_f32_e32 v184, v106, v248
	v_fmac_f32_e32 v185, v107, v249
	v_max_i32_e32 v246, 0, v28
	v_max_i32_e32 v247, 0, v20
	v_max_i32_e32 v248, 0, v29
	v_max_i32_e32 v249, 0, v21
	v_fmac_f32_e32 v184, v108, v246
	v_fmac_f32_e32 v185, v109, v247
	v_fmac_f32_e32 v184, v110, v248
	v_fmac_f32_e32 v185, v111, v249
	s_waitcnt lgkmcnt(6)
	v_mfma_f32_32x32x16_bf16 v[198:213], v[38:41], v[172:175], v[198:213]
	v_max_i32_e32 v246, 0, v30
	v_max_i32_e32 v247, 0, v22
	v_max_i32_e32 v248, 0, v31
	v_max_i32_e32 v249, 0, v23
	v_fmac_f32_e32 v184, v112, v246
	v_fmac_f32_e32 v185, v113, v247
	v_fmac_f32_e32 v184, v114, v248
	v_fmac_f32_e32 v185, v115, v249
	s_waitcnt lgkmcnt(5)
	v_mfma_f32_32x32x16_bf16 v[214:229], v[38:41], v[176:179], v[214:229]
	v_cmp_le_f32_e32 vcc, v250, v185
	s_mov_b64 s[52:53], vcc
	s_and_saveexec_b64 s[4:5], s[50:51]
	v_mov_b32_e32 v246, vcc_hi
	v_mov_b32_e32 v247, vcc_lo
	v_cndmask_b32_e64 v246, v246, v247, s[48:49]
	ds_write_b32 v162, v246
	s_or_b64 exec, exec, s[4:5]
	v_cmp_le_f32_e32 vcc, v156, v185
	s_andn2_b64 vcc, vcc, s[52:53]
	s_cbranch_vccz .Lp2_skip1
	v_mov_b32_e32 v246, vcc_hi
	v_mov_b32_e32 v247, vcc_lo
	v_cndmask_b32_e64 v246, v246, v247, s[48:49]
	s_and_saveexec_b64 s[4:5], vcc
	s_cbranch_execz .Lp2_join1
	v_and_b32_e32 v247, v246, v127
	v_bcnt_u32_b32 v247, v247, v119
	v_cmp_gt_u32_e32 vcc, s35, v247
	s_and_b64 exec, exec, vcc
	s_cbranch_execz .Lp2_join1
	v_cmp_gt_f32_e64 s[52:53], 0, v185
	v_not_b32_e32 v248, v185
	s_nop 0
	v_cndmask_b32_e64 v33, -|v185|, v248, s[52:53]
	v_lshl_add_u64 v[154:155], v[78:79], 0, s[0:1]
	v_lshl_add_u64 v[154:155], v[154:155], 0, v[32:33]
	v_lshl_add_u32 v248, v247, 3, v160
	ds_write_b64 v248, v[154:155] offset:2048

.Lp2_skip2:
	v_max_i32_e32 v246, 0, v8
	v_max_i32_e32 v247, 0, v0
	s_waitcnt lgkmcnt(5)
	v_mfma_f32_32x32x16_bf16 v[214:229], v[42:45], v[234:237], v[214:229]
	v_max_i32_e32 v248, 0, v9
	v_max_i32_e32 v249, 0, v1
	v_mul_f32_e32 v184, v100, v246
	v_mul_f32_e32 v185, v101, v247
	v_fmac_f32_e32 v184, v102, v248
	v_fmac_f32_e32 v185, v103, v249
	v_max_i32_e32 v246, 0, v10
	v_max_i32_e32 v247, 0, v2
	v_max_i32_e32 v248, 0, v11
	v_max_i32_e32 v249, 0, v3
	s_waitcnt lgkmcnt(4)
	v_mfma_f32_32x32x16_bf16 v[198:213], v[46:49], v[238:241], v[198:213]
	v_fmac_f32_e32 v184, v104, v246
	v_fmac_f32_e32 v185, v105, v247
	v_fmac_f32_e32 v184, v106, v248
	v_fmac_f32_e32 v185, v107, v249
	v_max_i32_e32 v246, 0, v12
	v_max_i32_e32 v247, 0, v4
	v_max_i32_e32 v248, 0, v13
	v_max_i32_e32 v249, 0, v5
	v_fmac_f32_e32 v184, v108, v246
	v_fmac_f32_e32 v185, v109, v247
	s_waitcnt lgkmcnt(3)
	v_mfma_f32_32x32x16_bf16 v[214:229], v[46:49], v[242:245], v[214:229]
	v_fmac_f32_e32 v184, v110, v248
	v_fmac_f32_e32 v185, v111, v249
	v_max_i32_e32 v246, 0, v14
	v_max_i32_e32 v247, 0, v6
	v_max_i32_e32 v248, 0, v15
	v_max_i32_e32 v249, 0, v7
	v_fmac_f32_e32 v184, v112, v246
	v_fmac_f32_e32 v185, v113, v247
	v_fmac_f32_e32 v184, v114, v248
	v_fmac_f32_e32 v185, v115, v249
	v_cmp_le_f32_e32 vcc, v250, v185
	s_mov_b64 s[52:53], vcc
	s_and_saveexec_b64 s[4:5], s[50:51]
	v_mov_b32_e32 v246, vcc_hi
	v_mov_b32_e32 v247, vcc_lo
	v_cndmask_b32_e64 v246, v246, v247, s[48:49]
	ds_write_b32 v162, v246 offset:4
	s_or_b64 exec, exec, s[4:5]
	v_cmp_le_f32_e32 vcc, v156, v185
	s_andn2_b64 vcc, vcc, s[52:53]
	s_cbranch_vccz .Lp2_skip3
	v_mov_b32_e32 v246, vcc_hi
	v_mov_b32_e32 v247, vcc_lo
	v_cndmask_b32_e64 v246, v246, v247, s[48:49]
	s_and_saveexec_b64 s[4:5], vcc
	s_cbranch_execz .Lp2_join3
	v_and_b32_e32 v247, v246, v127
	v_bcnt_u32_b32 v247, v247, v119
	v_cmp_gt_u32_e32 vcc, s35, v247
	s_and_b64 exec, exec, vcc
	s_cbranch_execz .Lp2_join3
	v_cmp_gt_f32_e64 s[52:53], 0, v185
	v_not_b32_e32 v248, v185
	s_nop 0
	v_cndmask_b32_e64 v33, -|v185|, v248, s[52:53]
	v_lshl_add_u64 v[154:155], v[96:97], 0, s[0:1]
	v_lshl_add_u64 v[154:155], v[154:155], 0, v[32:33]
	v_lshl_add_u32 v248, v247, 3, v160
	ds_write_b64 v248, v[154:155] offset:2048

.Lp2_c2:
	ds_read_b128 v[164:167], v99 offset:0
	ds_read_b128 v[168:171], v99 offset:4096
	ds_read_b128 v[172:175], v99 offset:1024
	ds_read_b128 v[176:179], v99 offset:5120
	ds_read_b128 v[230:233], v99 offset:2048
	ds_read_b128 v[234:237], v99 offset:6144
	ds_read_b128 v[238:241], v99 offset:3072
	ds_read_b128 v[242:245], v99 offset:7168
	v_max_i32_e32 v246, 0, v206
	v_max_i32_e32 v247, 0, v198
	v_max_i32_e32 v248, 0, v207
	v_max_i32_e32 v249, 0, v199
	s_waitcnt lgkmcnt(7)
	v_mfma_f32_32x32x16_bf16 v[16:31], v[34:37], v[164:167], 0
	v_mul_f32_e32 v184, v100, v246
	v_mul_f32_e32 v185, v101, v247
	v_fmac_f32_e32 v184, v102, v248
	v_fmac_f32_e32 v185, v103, v249
	v_max_i32_e32 v246, 0, v208
	v_max_i32_e32 v247, 0, v200
	v_max_i32_e32 v248, 0, v209
	v_max_i32_e32 v249, 0, v201
	v_fmac_f32_e32 v184, v104, v246
	v_fmac_f32_e32 v185, v105, v247
	s_waitcnt lgkmcnt(6)
	v_mfma_f32_32x32x16_bf16 v[0:15], v[34:37], v[168:171], 0
	s_waitcnt vmcnt(3)
	ds_write_b128 v140, v[58:61] offset:8192
	s_add_i32 s4, s18, 5
	s_min_i32 s4, s4, s14
	v_mad_i64_i32 v[164:165], s[4:5], s4, v193, v[116:117]
	global_load_dwordx4 v[58:61], v[164:165], off
	v_fmac_f32_e32 v184, v106, v248
	v_fmac_f32_e32 v185, v107, v249
	v_max_i32_e32 v246, 0, v210
	v_max_i32_e32 v247, 0, v202
	v_max_i32_e32 v248, 0, v211
	v_max_i32_e32 v249, 0, v203
	v_fmac_f32_e32 v184, v108, v246
	v_fmac_f32_e32 v185, v109, v247
	v_fmac_f32_e32 v184, v110, v248
	v_fmac_f32_e32 v185, v111, v249
	s_waitcnt lgkmcnt(6)
	v_mfma_f32_32x32x16_bf16 v[16:31], v[38:41], v[172:175], v[16:31]
	v_max_i32_e32 v246, 0, v212
	v_max_i32_e32 v247, 0, v204
	v_max_i32_e32 v248, 0, v213
	v_max_i32_e32 v249, 0, v205
	v_fmac_f32_e32 v184, v112, v246
	v_fmac_f32_e32 v185, v113, v247
	v_fmac_f32_e32 v184, v114, v248
	v_fmac_f32_e32 v185, v115, v249
	s_waitcnt lgkmcnt(5)
	v_mfma_f32_32x32x16_bf16 v[0:15], v[38:41], v[176:179], v[0:15]
	v_cmp_le_f32_e32 vcc, v250, v185
	s_mov_b64 s[52:53], vcc
	s_and_saveexec_b64 s[4:5], s[50:51]
	v_mov_b32_e32 v246, vcc_hi
	v_mov_b32_e32 v247, vcc_lo
	v_cndmask_b32_e64 v246, v246, v247, s[48:49]
	ds_write_b32 v162, v246 offset:8
	s_or_b64 exec, exec, s[4:5]
	v_cmp_le_f32_e32 vcc, v156, v185
	s_andn2_b64 vcc, vcc, s[52:53]
	s_cbranch_vccz .Lp2_skip5
	v_mov_b32_e32 v246, vcc_hi
	v_mov_b32_e32 v247, vcc_lo
	v_cndmask_b32_e64 v246, v246, v247, s[48:49]
	s_and_saveexec_b64 s[4:5], vcc
	s_cbranch_execz .Lp2_join5
	v_and_b32_e32 v247, v246, v127
	v_bcnt_u32_b32 v247, v247, v119
	v_cmp_gt_u32_e32 vcc, s35, v247
	s_and_b64 exec, exec, vcc
	s_cbranch_execz .Lp2_join5
	v_cmp_gt_f32_e64 s[52:53], 0, v185
	v_not_b32_e32 v248, v185
	s_nop 0
	v_cndmask_b32_e64 v33, -|v185|, v248, s[52:53]
	v_lshl_add_u64 v[154:155], v[92:93], 0, s[0:1]
	v_lshl_add_u64 v[154:155], v[154:155], 0, v[32:33]
	v_lshl_add_u32 v248, v247, 3, v160
	ds_write_b64 v248, v[154:155] offset:2048

.Lp2_skip6:
	v_max_i32_e32 v246, 0, v222
	v_max_i32_e32 v247, 0, v214
	s_waitcnt lgkmcnt(5)
	v_mfma_f32_32x32x16_bf16 v[0:15], v[42:45], v[234:237], v[0:15]
	v_max_i32_e32 v248, 0, v223
	v_max_i32_e32 v249, 0, v215
	v_mul_f32_e32 v184, v100, v246
	v_mul_f32_e32 v185, v101, v247
	v_fmac_f32_e32 v184, v102, v248
	v_fmac_f32_e32 v185, v103, v249
	v_max_i32_e32 v246, 0, v224
	v_max_i32_e32 v247, 0, v216
	v_max_i32_e32 v248, 0, v225
	v_max_i32_e32 v249, 0, v217
	s_waitcnt lgkmcnt(4)
	v_mfma_f32_32x32x16_bf16 v[16:31], v[46:49], v[238:241], v[16:31]
	v_fmac_f32_e32 v184, v104, v246
	v_fmac_f32_e32 v185, v105, v247
	v_fmac_f32_e32 v184, v106, v248
	v_fmac_f32_e32 v185, v107, v249
	v_max_i32_e32 v246, 0, v226
	v_max_i32_e32 v247, 0, v218
	v_max_i32_e32 v248, 0, v227
	v_max_i32_e32 v249, 0, v219
	v_fmac_f32_e32 v184, v108, v246
	v_fmac_f32_e32 v185, v109, v247
	s_waitcnt lgkmcnt(3)
	v_mfma_f32_32x32x16_bf16 v[0:15], v[46:49], v[242:245], v[0:15]
	v_fmac_f32_e32 v184, v110, v248
	v_fmac_f32_e32 v185, v111, v249
	v_max_i32_e32 v246, 0, v228
	v_max_i32_e32 v247, 0, v220
	v_max_i32_e32 v248, 0, v229
	v_max_i32_e32 v249, 0, v221
	v_fmac_f32_e32 v184, v112, v246
	v_fmac_f32_e32 v185, v113, v247
	v_fmac_f32_e32 v184, v114, v248
	v_fmac_f32_e32 v185, v115, v249
	v_cmp_le_f32_e32 vcc, v250, v185
	s_mov_b64 s[52:53], vcc
	s_and_saveexec_b64 s[4:5], s[50:51]
	v_mov_b32_e32 v246, vcc_hi
	v_mov_b32_e32 v247, vcc_lo
	v_cndmask_b32_e64 v246, v246, v247, s[48:49]
	ds_write_b32 v162, v246 offset:12
	s_or_b64 exec, exec, s[4:5]
	v_cmp_le_f32_e32 vcc, v156, v185
	s_andn2_b64 vcc, vcc, s[52:53]
	s_cbranch_vccz .Lp2_skip7
	v_mov_b32_e32 v246, vcc_hi
	v_mov_b32_e32 v247, vcc_lo
	v_cndmask_b32_e64 v246, v246, v247, s[48:49]
	s_and_saveexec_b64 s[4:5], vcc
	s_cbranch_execz .Lp2_join7
	v_and_b32_e32 v247, v246, v127
	v_bcnt_u32_b32 v247, v247, v119
	v_cmp_gt_u32_e32 vcc, s35, v247
	s_and_b64 exec, exec, vcc
	s_cbranch_execz .Lp2_join7
	v_cmp_gt_f32_e64 s[52:53], 0, v185
	v_not_b32_e32 v248, v185
	s_nop 0
	v_cndmask_b32_e64 v33, -|v185|, v248, s[52:53]
	v_lshl_add_u64 v[154:155], v[94:95], 0, s[0:1]
	v_lshl_add_u64 v[154:155], v[154:155], 0, v[32:33]
	v_lshl_add_u32 v248, v247, 3, v160
	ds_write_b64 v248, v[154:155] offset:2048

.Lp2_c3:
	ds_read_b128 v[164:167], v99 offset:8192
	ds_read_b128 v[168:171], v99 offset:12288
	ds_read_b128 v[172:175], v99 offset:9216
	ds_read_b128 v[176:179], v99 offset:13312
	ds_read_b128 v[230:233], v99 offset:10240
	ds_read_b128 v[234:237], v99 offset:14336
	ds_read_b128 v[238:241], v99 offset:11264
	ds_read_b128 v[242:245], v99 offset:15360
	v_max_i32_e32 v246, 0, v24
	v_max_i32_e32 v247, 0, v16
	v_max_i32_e32 v248, 0, v25
	v_max_i32_e32 v249, 0, v17
	s_waitcnt lgkmcnt(7)
	v_mfma_f32_32x32x16_bf16 v[198:213], v[34:37], v[164:167], 0
	v_mul_f32_e32 v184, v100, v246
	v_mul_f32_e32 v185, v101, v247
	v_fmac_f32_e32 v184, v102, v248
	v_fmac_f32_e32 v185, v103, v249
	v_max_i32_e32 v246, 0, v26
	v_max_i32_e32 v247, 0, v18
	v_max_i32_e32 v248, 0, v27
	v_max_i32_e32 v249, 0, v19
	v_fmac_f32_e32 v184, v104, v246
	v_fmac_f32_e32 v185, v105, v247
	s_waitcnt lgkmcnt(6)
	v_mfma_f32_32x32x16_bf16 v[214:229], v[34:37], v[168:171], 0
	s_waitcnt vmcnt(3)
	ds_write_b128 v140, v[62:65]
	s_add_i32 s4, s18, 5
	s_min_i32 s4, s4, s14
	v_mad_i64_i32 v[164:165], s[4:5], s4, v193, v[116:117]
	global_load_dwordx4 v[62:65], v[164:165], off
	v_fmac_f32_e32 v184, v106, v248
	v_fmac_f32_e32 v185, v107, v249
	v_max_i32_e32 v246, 0, v28
	v_max_i32_e32 v247, 0, v20
	v_max_i32_e32 v248, 0, v29
	v_max_i32_e32 v249, 0, v21
	v_fmac_f32_e32 v184, v108, v246
	v_fmac_f32_e32 v185, v109, v247
	v_fmac_f32_e32 v184, v110, v248
	v_fmac_f32_e32 v185, v111, v249
	s_waitcnt lgkmcnt(6)
	v_mfma_f32_32x32x16_bf16 v[198:213], v[38:41], v[172:175], v[198:213]
	v_max_i32_e32 v246, 0, v30
	v_max_i32_e32 v247, 0, v22
	v_max_i32_e32 v248, 0, v31
	v_max_i32_e32 v249, 0, v23
	v_fmac_f32_e32 v184, v112, v246
	v_fmac_f32_e32 v185, v113, v247
	v_fmac_f32_e32 v184, v114, v248
	v_fmac_f32_e32 v185, v115, v249
	s_waitcnt lgkmcnt(5)
	v_mfma_f32_32x32x16_bf16 v[214:229], v[38:41], v[176:179], v[214:229]
	v_cmp_le_f32_e32 vcc, v250, v185
	s_mov_b64 s[52:53], vcc
	s_and_saveexec_b64 s[4:5], s[50:51]
	v_mov_b32_e32 v246, vcc_hi
	v_mov_b32_e32 v247, vcc_lo
	v_cndmask_b32_e64 v246, v246, v247, s[48:49]
	ds_write_b32 v162, v246 offset:16
	s_or_b64 exec, exec, s[4:5]
	v_cmp_le_f32_e32 vcc, v156, v185
	s_andn2_b64 vcc, vcc, s[52:53]
	s_cbranch_vccz .Lp2_skip9
	v_mov_b32_e32 v246, vcc_hi
	v_mov_b32_e32 v247, vcc_lo
	v_cndmask_b32_e64 v246, v246, v247, s[48:49]
	s_and_saveexec_b64 s[4:5], vcc
	s_cbranch_execz .Lp2_join9
	v_and_b32_e32 v247, v246, v127
	v_bcnt_u32_b32 v247, v247, v119
	v_cmp_gt_u32_e32 vcc, s35, v247
	s_and_b64 exec, exec, vcc
	s_cbranch_execz .Lp2_join9
	v_cmp_gt_f32_e64 s[52:53], 0, v185
	v_not_b32_e32 v248, v185
	s_nop 0
	v_cndmask_b32_e64 v33, -|v185|, v248, s[52:53]
	v_lshl_add_u64 v[154:155], v[90:91], 0, s[0:1]
	v_lshl_add_u64 v[154:155], v[154:155], 0, v[32:33]
	v_lshl_add_u32 v248, v247, 3, v160
	ds_write_b64 v248, v[154:155] offset:2048

.Lp2_skip10:
	v_max_i32_e32 v246, 0, v8
	v_max_i32_e32 v247, 0, v0
	s_waitcnt lgkmcnt(5)
	v_mfma_f32_32x32x16_bf16 v[214:229], v[42:45], v[234:237], v[214:229]
	v_max_i32_e32 v248, 0, v9
	v_max_i32_e32 v249, 0, v1
	v_mul_f32_e32 v184, v100, v246
	v_mul_f32_e32 v185, v101, v247
	v_fmac_f32_e32 v184, v102, v248
	v_fmac_f32_e32 v185, v103, v249
	v_max_i32_e32 v246, 0, v10
	v_max_i32_e32 v247, 0, v2
	v_max_i32_e32 v248, 0, v11
	v_max_i32_e32 v249, 0, v3
	s_waitcnt lgkmcnt(4)
	v_mfma_f32_32x32x16_bf16 v[198:213], v[46:49], v[238:241], v[198:213]
	v_fmac_f32_e32 v184, v104, v246
	v_fmac_f32_e32 v185, v105, v247
	v_fmac_f32_e32 v184, v106, v248
	v_fmac_f32_e32 v185, v107, v249
	v_max_i32_e32 v246, 0, v12
	v_max_i32_e32 v247, 0, v4
	v_max_i32_e32 v248, 0, v13
	v_max_i32_e32 v249, 0, v5
	v_fmac_f32_e32 v184, v108, v246
	v_fmac_f32_e32 v185, v109, v247
	s_waitcnt lgkmcnt(3)
	v_mfma_f32_32x32x16_bf16 v[214:229], v[46:49], v[242:245], v[214:229]
	v_fmac_f32_e32 v184, v110, v248
	v_fmac_f32_e32 v185, v111, v249
	v_max_i32_e32 v246, 0, v14
	v_max_i32_e32 v247, 0, v6
	v_max_i32_e32 v248, 0, v15
	v_max_i32_e32 v249, 0, v7
	v_fmac_f32_e32 v184, v112, v246
	v_fmac_f32_e32 v185, v113, v247
	v_fmac_f32_e32 v184, v114, v248
	v_fmac_f32_e32 v185, v115, v249
	v_cmp_le_f32_e32 vcc, v250, v185
	s_mov_b64 s[52:53], vcc
	s_and_saveexec_b64 s[4:5], s[50:51]
	v_mov_b32_e32 v246, vcc_hi
	v_mov_b32_e32 v247, vcc_lo
	v_cndmask_b32_e64 v246, v246, v247, s[48:49]
	ds_write_b32 v162, v246 offset:20
	s_or_b64 exec, exec, s[4:5]
	v_cmp_le_f32_e32 vcc, v156, v185
	s_andn2_b64 vcc, vcc, s[52:53]
	s_cbranch_vccz .Lp2_skip11
	v_mov_b32_e32 v246, vcc_hi
	v_mov_b32_e32 v247, vcc_lo
	v_cndmask_b32_e64 v246, v246, v247, s[48:49]
	s_and_saveexec_b64 s[4:5], vcc
	s_cbranch_execz .Lp2_join11
	v_and_b32_e32 v247, v246, v127
	v_bcnt_u32_b32 v247, v247, v119
	v_cmp_gt_u32_e32 vcc, s35, v247
	s_and_b64 exec, exec, vcc
	s_cbranch_execz .Lp2_join11
	v_cmp_gt_f32_e64 s[52:53], 0, v185
	v_not_b32_e32 v248, v185
	s_nop 0
	v_cndmask_b32_e64 v33, -|v185|, v248, s[52:53]
	v_lshl_add_u64 v[154:155], v[88:89], 0, s[0:1]
	v_lshl_add_u64 v[154:155], v[154:155], 0, v[32:33]
	v_lshl_add_u32 v248, v247, 3, v160
	ds_write_b64 v248, v[154:155] offset:2048

.Lp2_c0:
	ds_read_b128 v[164:167], v99 offset:0
	ds_read_b128 v[168:171], v99 offset:4096
	ds_read_b128 v[172:175], v99 offset:1024
	ds_read_b128 v[176:179], v99 offset:5120
	ds_read_b128 v[230:233], v99 offset:2048
	ds_read_b128 v[234:237], v99 offset:6144
	ds_read_b128 v[238:241], v99 offset:3072
	ds_read_b128 v[242:245], v99 offset:7168
	v_max_i32_e32 v246, 0, v206
	v_max_i32_e32 v247, 0, v198
	v_max_i32_e32 v248, 0, v207
	v_max_i32_e32 v249, 0, v199
	s_waitcnt lgkmcnt(7)
	v_mfma_f32_32x32x16_bf16 v[16:31], v[34:37], v[164:167], 0
	v_mul_f32_e32 v184, v100, v246
	v_mul_f32_e32 v185, v101, v247
	v_fmac_f32_e32 v184, v102, v248
	v_fmac_f32_e32 v185, v103, v249
	v_max_i32_e32 v246, 0, v208
	v_max_i32_e32 v247, 0, v200
	v_max_i32_e32 v248, 0, v209
	v_max_i32_e32 v249, 0, v201
	v_fmac_f32_e32 v184, v104, v246
	v_fmac_f32_e32 v185, v105, v247
	s_waitcnt lgkmcnt(6)
	v_mfma_f32_32x32x16_bf16 v[0:15], v[34:37], v[168:171], 0
	s_waitcnt vmcnt(3)
	ds_write_b128 v140, v[50:53] offset:8192
	s_add_i32 s4, s18, 5
	s_min_i32 s4, s4, s14
	v_mad_i64_i32 v[164:165], s[4:5], s4, v193, v[116:117]
	global_load_dwordx4 v[50:53], v[164:165], off
	v_fmac_f32_e32 v184, v106, v248
	v_fmac_f32_e32 v185, v107, v249
	v_max_i32_e32 v246, 0, v210
	v_max_i32_e32 v247, 0, v202
	v_max_i32_e32 v248, 0, v211
	v_max_i32_e32 v249, 0, v203
	v_fmac_f32_e32 v184, v108, v246
	v_fmac_f32_e32 v185, v109, v247
	v_fmac_f32_e32 v184, v110, v248
	v_fmac_f32_e32 v185, v111, v249
	s_waitcnt lgkmcnt(6)
	v_mfma_f32_32x32x16_bf16 v[16:31], v[38:41], v[172:175], v[16:31]
	v_max_i32_e32 v246, 0, v212
	v_max_i32_e32 v247, 0, v204
	v_max_i32_e32 v248, 0, v213
	v_max_i32_e32 v249, 0, v205
	v_fmac_f32_e32 v184, v112, v246
	v_fmac_f32_e32 v185, v113, v247
	v_fmac_f32_e32 v184, v114, v248
	v_fmac_f32_e32 v185, v115, v249
	s_waitcnt lgkmcnt(5)
	v_mfma_f32_32x32x16_bf16 v[0:15], v[38:41], v[176:179], v[0:15]
	v_cmp_le_f32_e32 vcc, v250, v185
	s_mov_b64 s[52:53], vcc
	s_and_saveexec_b64 s[4:5], s[50:51]
	v_mov_b32_e32 v246, vcc_hi
	v_mov_b32_e32 v247, vcc_lo
	v_cndmask_b32_e64 v246, v246, v247, s[48:49]
	ds_write_b32 v162, v246 offset:24
	s_or_b64 exec, exec, s[4:5]
	v_cmp_le_f32_e32 vcc, v156, v185
	s_andn2_b64 vcc, vcc, s[52:53]
	s_cbranch_vccz .Lp2_skip13
	v_mov_b32_e32 v246, vcc_hi
	v_mov_b32_e32 v247, vcc_lo
	v_cndmask_b32_e64 v246, v246, v247, s[48:49]
	s_and_saveexec_b64 s[4:5], vcc
	s_cbranch_execz .Lp2_join13
	v_and_b32_e32 v247, v246, v127
	v_bcnt_u32_b32 v247, v247, v119
	v_cmp_gt_u32_e32 vcc, s35, v247
	s_and_b64 exec, exec, vcc
	s_cbranch_execz .Lp2_join13
	v_cmp_gt_f32_e64 s[52:53], 0, v185
	v_not_b32_e32 v248, v185
	s_nop 0
	v_cndmask_b32_e64 v33, -|v185|, v248, s[52:53]
	v_lshl_add_u64 v[154:155], v[86:87], 0, s[0:1]
	v_lshl_add_u64 v[154:155], v[154:155], 0, v[32:33]
	v_lshl_add_u32 v248, v247, 3, v160
	ds_write_b64 v248, v[154:155] offset:2048

.Lp2_skip14:
	v_max_i32_e32 v246, 0, v222
	v_max_i32_e32 v247, 0, v214
	s_waitcnt lgkmcnt(5)
	v_mfma_f32_32x32x16_bf16 v[0:15], v[42:45], v[234:237], v[0:15]
	v_max_i32_e32 v248, 0, v223
	v_max_i32_e32 v249, 0, v215
	v_mul_f32_e32 v184, v100, v246
	v_mul_f32_e32 v185, v101, v247
	v_fmac_f32_e32 v184, v102, v248
	v_fmac_f32_e32 v185, v103, v249
	v_max_i32_e32 v246, 0, v224
	v_max_i32_e32 v247, 0, v216
	v_max_i32_e32 v248, 0, v225
	v_max_i32_e32 v249, 0, v217
	s_waitcnt lgkmcnt(4)
	v_mfma_f32_32x32x16_bf16 v[16:31], v[46:49], v[238:241], v[16:31]
	v_fmac_f32_e32 v184, v104, v246
	v_fmac_f32_e32 v185, v105, v247
	v_fmac_f32_e32 v184, v106, v248
	v_fmac_f32_e32 v185, v107, v249
	v_max_i32_e32 v246, 0, v226
	v_max_i32_e32 v247, 0, v218
	v_max_i32_e32 v248, 0, v227
	v_max_i32_e32 v249, 0, v219
	v_fmac_f32_e32 v184, v108, v246
	v_fmac_f32_e32 v185, v109, v247
	s_waitcnt lgkmcnt(3)
	v_mfma_f32_32x32x16_bf16 v[0:15], v[46:49], v[242:245], v[0:15]
	v_fmac_f32_e32 v184, v110, v248
	v_fmac_f32_e32 v185, v111, v249
	v_max_i32_e32 v246, 0, v228
	v_max_i32_e32 v247, 0, v220
	v_max_i32_e32 v248, 0, v229
	v_max_i32_e32 v249, 0, v221
	v_fmac_f32_e32 v184, v112, v246
	v_fmac_f32_e32 v185, v113, v247
	v_fmac_f32_e32 v184, v114, v248
	v_fmac_f32_e32 v185, v115, v249
	v_cmp_le_f32_e32 vcc, v250, v185
	s_mov_b64 s[52:53], vcc
	s_and_saveexec_b64 s[4:5], s[50:51]
	v_mov_b32_e32 v246, vcc_hi
	v_mov_b32_e32 v247, vcc_lo
	v_cndmask_b32_e64 v246, v246, v247, s[48:49]
	ds_write_b32 v162, v246 offset:28
	s_or_b64 exec, exec, s[4:5]
	v_cmp_le_f32_e32 vcc, v156, v185
	s_andn2_b64 vcc, vcc, s[52:53]
	s_cbranch_vccz .Lp2_skip15
	v_mov_b32_e32 v246, vcc_hi
	v_mov_b32_e32 v247, vcc_lo
	v_cndmask_b32_e64 v246, v246, v247, s[48:49]
	s_and_saveexec_b64 s[4:5], vcc
	s_cbranch_execz .Lp2_join15
	v_and_b32_e32 v247, v246, v127
	v_bcnt_u32_b32 v247, v247, v119
	v_cmp_gt_u32_e32 vcc, s35, v247
	s_and_b64 exec, exec, vcc
	s_cbranch_execz .Lp2_join15
	v_cmp_gt_f32_e64 s[52:53], 0, v185
	v_not_b32_e32 v248, v185
	s_nop 0
	v_cndmask_b32_e64 v33, -|v185|, v248, s[52:53]
	v_lshl_add_u64 v[154:155], v[84:85], 0, s[0:1]
	v_lshl_add_u64 v[154:155], v[154:155], 0, v[32:33]
	v_lshl_add_u32 v248, v247, 3, v160
	ds_write_b64 v248, v[154:155] offset:2048

.Lp2_drain0:
	v_max_i32_e32 v246, 0, v24
	v_max_i32_e32 v247, 0, v16
	v_max_i32_e32 v248, 0, v25
	v_max_i32_e32 v249, 0, v17
	v_mul_f32_e32 v184, v100, v246
	v_mul_f32_e32 v185, v101, v247
	v_fmac_f32_e32 v184, v102, v248
	v_fmac_f32_e32 v185, v103, v249
	v_max_i32_e32 v246, 0, v26
	v_max_i32_e32 v247, 0, v18
	v_max_i32_e32 v248, 0, v27
	v_max_i32_e32 v249, 0, v19
	v_fmac_f32_e32 v184, v104, v246
	v_fmac_f32_e32 v185, v105, v247
	v_fmac_f32_e32 v184, v106, v248
	v_fmac_f32_e32 v185, v107, v249
	v_max_i32_e32 v246, 0, v28
	v_max_i32_e32 v247, 0, v20
	v_max_i32_e32 v248, 0, v29
	v_max_i32_e32 v249, 0, v21
	v_fmac_f32_e32 v184, v108, v246
	v_fmac_f32_e32 v185, v109, v247
	v_fmac_f32_e32 v184, v110, v248
	v_fmac_f32_e32 v185, v111, v249
	v_max_i32_e32 v246, 0, v30
	v_max_i32_e32 v247, 0, v22
	v_max_i32_e32 v248, 0, v31
	v_max_i32_e32 v249, 0, v23
	v_fmac_f32_e32 v184, v112, v246
	v_fmac_f32_e32 v185, v113, v247
	v_fmac_f32_e32 v184, v114, v248
	v_fmac_f32_e32 v185, v115, v249
	v_cmp_le_f32_e32 vcc, v250, v185
	s_mov_b64 s[52:53], vcc
	s_and_saveexec_b64 s[4:5], s[50:51]
	v_mov_b32_e32 v246, vcc_hi
	v_mov_b32_e32 v247, vcc_lo
	v_cndmask_b32_e64 v246, v246, v247, s[48:49]
	ds_write_b32 v162, v246
	s_or_b64 exec, exec, s[4:5]
	v_cmp_le_f32_e32 vcc, v156, v185
	s_andn2_b64 vcc, vcc, s[52:53]
	s_cbranch_vccz .Lp2_skip17
	v_mov_b32_e32 v246, vcc_hi
	v_mov_b32_e32 v247, vcc_lo
	v_cndmask_b32_e64 v246, v246, v247, s[48:49]
	s_and_saveexec_b64 s[4:5], vcc
	s_cbranch_execz .Lp2_join17
	v_and_b32_e32 v247, v246, v127
	v_bcnt_u32_b32 v247, v247, v119
	v_cmp_gt_u32_e32 vcc, s35, v247
	s_and_b64 exec, exec, vcc
	s_cbranch_execz .Lp2_join17
	v_cmp_gt_f32_e64 s[52:53], 0, v185
	v_not_b32_e32 v248, v185
	s_nop 0
	v_cndmask_b32_e64 v33, -|v185|, v248, s[52:53]
	v_lshl_add_u64 v[154:155], v[78:79], 0, s[0:1]
	v_lshl_add_u64 v[154:155], v[154:155], 0, v[32:33]
	v_lshl_add_u32 v248, v247, 3, v160
	ds_write_b64 v248, v[154:155] offset:2048

.Lp2_skip18:
	v_max_i32_e32 v246, 0, v8
	v_max_i32_e32 v247, 0, v0
	v_max_i32_e32 v248, 0, v9
	v_max_i32_e32 v249, 0, v1
	v_mul_f32_e32 v184, v100, v246
	v_mul_f32_e32 v185, v101, v247
	v_fmac_f32_e32 v184, v102, v248
	v_fmac_f32_e32 v185, v103, v249
	v_max_i32_e32 v246, 0, v10
	v_max_i32_e32 v247, 0, v2
	v_max_i32_e32 v248, 0, v11
	v_max_i32_e32 v249, 0, v3
	v_fmac_f32_e32 v184, v104, v246
	v_fmac_f32_e32 v185, v105, v247
	v_fmac_f32_e32 v184, v106, v248
	v_fmac_f32_e32 v185, v107, v249
	v_max_i32_e32 v246, 0, v12
	v_max_i32_e32 v247, 0, v4
	v_max_i32_e32 v248, 0, v13
	v_max_i32_e32 v249, 0, v5
	v_fmac_f32_e32 v184, v108, v246
	v_fmac_f32_e32 v185, v109, v247
	v_fmac_f32_e32 v184, v110, v248
	v_fmac_f32_e32 v185, v111, v249
	v_max_i32_e32 v246, 0, v14
	v_max_i32_e32 v247, 0, v6
	v_max_i32_e32 v248, 0, v15
	v_max_i32_e32 v249, 0, v7
	v_fmac_f32_e32 v184, v112, v246
	v_fmac_f32_e32 v185, v113, v247
	v_fmac_f32_e32 v184, v114, v248
	v_fmac_f32_e32 v185, v115, v249
	v_cmp_le_f32_e32 vcc, v250, v185
	s_mov_b64 s[52:53], vcc
	s_and_saveexec_b64 s[4:5], s[50:51]
	v_mov_b32_e32 v246, vcc_hi
	v_mov_b32_e32 v247, vcc_lo
	v_cndmask_b32_e64 v246, v246, v247, s[48:49]
	ds_write_b32 v162, v246 offset:4
	s_or_b64 exec, exec, s[4:5]
	v_cmp_le_f32_e32 vcc, v156, v185
	s_andn2_b64 vcc, vcc, s[52:53]
	s_cbranch_vccz .Lp2_skip19
	v_mov_b32_e32 v246, vcc_hi
	v_mov_b32_e32 v247, vcc_lo
	v_cndmask_b32_e64 v246, v246, v247, s[48:49]
	s_and_saveexec_b64 s[4:5], vcc
	s_cbranch_execz .Lp2_join19
	v_and_b32_e32 v247, v246, v127
	v_bcnt_u32_b32 v247, v247, v119
	v_cmp_gt_u32_e32 vcc, s35, v247
	s_and_b64 exec, exec, vcc
	s_cbranch_execz .Lp2_join19
	v_cmp_gt_f32_e64 s[52:53], 0, v185
	v_not_b32_e32 v248, v185
	s_nop 0
	v_cndmask_b32_e64 v33, -|v185|, v248, s[52:53]
	v_lshl_add_u64 v[154:155], v[96:97], 0, s[0:1]
	v_lshl_add_u64 v[154:155], v[154:155], 0, v[32:33]
	v_lshl_add_u32 v248, v247, 3, v160
	ds_write_b64 v248, v[154:155] offset:2048

.Lp2_drain1:
	v_max_i32_e32 v246, 0, v206
	v_max_i32_e32 v247, 0, v198
	v_max_i32_e32 v248, 0, v207
	v_max_i32_e32 v249, 0, v199
	v_mul_f32_e32 v184, v100, v246
	v_mul_f32_e32 v185, v101, v247
	v_fmac_f32_e32 v184, v102, v248
	v_fmac_f32_e32 v185, v103, v249
	v_max_i32_e32 v246, 0, v208
	v_max_i32_e32 v247, 0, v200
	v_max_i32_e32 v248, 0, v209
	v_max_i32_e32 v249, 0, v201
	v_fmac_f32_e32 v184, v104, v246
	v_fmac_f32_e32 v185, v105, v247
	v_fmac_f32_e32 v184, v106, v248
	v_fmac_f32_e32 v185, v107, v249
	v_max_i32_e32 v246, 0, v210
	v_max_i32_e32 v247, 0, v202
	v_max_i32_e32 v248, 0, v211
	v_max_i32_e32 v249, 0, v203
	v_fmac_f32_e32 v184, v108, v246
	v_fmac_f32_e32 v185, v109, v247
	v_fmac_f32_e32 v184, v110, v248
	v_fmac_f32_e32 v185, v111, v249
	v_max_i32_e32 v246, 0, v212
	v_max_i32_e32 v247, 0, v204
	v_max_i32_e32 v248, 0, v213
	v_max_i32_e32 v249, 0, v205
	v_fmac_f32_e32 v184, v112, v246
	v_fmac_f32_e32 v185, v113, v247
	v_fmac_f32_e32 v184, v114, v248
	v_fmac_f32_e32 v185, v115, v249
	v_cmp_le_f32_e32 vcc, v250, v185
	s_mov_b64 s[52:53], vcc
	s_and_saveexec_b64 s[4:5], s[50:51]
	v_mov_b32_e32 v246, vcc_hi
	v_mov_b32_e32 v247, vcc_lo
	v_cndmask_b32_e64 v246, v246, v247, s[48:49]
	ds_write_b32 v162, v246 offset:8
	s_or_b64 exec, exec, s[4:5]
	v_cmp_le_f32_e32 vcc, v156, v185
	s_andn2_b64 vcc, vcc, s[52:53]
	s_cbranch_vccz .Lp2_skip21
	v_mov_b32_e32 v246, vcc_hi
	v_mov_b32_e32 v247, vcc_lo
	v_cndmask_b32_e64 v246, v246, v247, s[48:49]
	s_and_saveexec_b64 s[4:5], vcc
	s_cbranch_execz .Lp2_join21
	v_and_b32_e32 v247, v246, v127
	v_bcnt_u32_b32 v247, v247, v119
	v_cmp_gt_u32_e32 vcc, s35, v247
	s_and_b64 exec, exec, vcc
	s_cbranch_execz .Lp2_join21
	v_cmp_gt_f32_e64 s[52:53], 0, v185
	v_not_b32_e32 v248, v185
	s_nop 0
	v_cndmask_b32_e64 v33, -|v185|, v248, s[52:53]
	v_lshl_add_u64 v[154:155], v[92:93], 0, s[0:1]
	v_lshl_add_u64 v[154:155], v[154:155], 0, v[32:33]
	v_lshl_add_u32 v248, v247, 3, v160
	ds_write_b64 v248, v[154:155] offset:2048

.Lp2_skip22:
	v_max_i32_e32 v246, 0, v222
	v_max_i32_e32 v247, 0, v214
	v_max_i32_e32 v248, 0, v223
	v_max_i32_e32 v249, 0, v215
	v_mul_f32_e32 v184, v100, v246
	v_mul_f32_e32 v185, v101, v247
	v_fmac_f32_e32 v184, v102, v248
	v_fmac_f32_e32 v185, v103, v249
	v_max_i32_e32 v246, 0, v224
	v_max_i32_e32 v247, 0, v216
	v_max_i32_e32 v248, 0, v225
	v_max_i32_e32 v249, 0, v217
	v_fmac_f32_e32 v184, v104, v246
	v_fmac_f32_e32 v185, v105, v247
	v_fmac_f32_e32 v184, v106, v248
	v_fmac_f32_e32 v185, v107, v249
	v_max_i32_e32 v246, 0, v226
	v_max_i32_e32 v247, 0, v218
	v_max_i32_e32 v248, 0, v227
	v_max_i32_e32 v249, 0, v219
	v_fmac_f32_e32 v184, v108, v246
	v_fmac_f32_e32 v185, v109, v247
	v_fmac_f32_e32 v184, v110, v248
	v_fmac_f32_e32 v185, v111, v249
	v_max_i32_e32 v246, 0, v228
	v_max_i32_e32 v247, 0, v220
	v_max_i32_e32 v248, 0, v229
	v_max_i32_e32 v249, 0, v221
	v_fmac_f32_e32 v184, v112, v246
	v_fmac_f32_e32 v185, v113, v247
	v_fmac_f32_e32 v184, v114, v248
	v_fmac_f32_e32 v185, v115, v249
	v_cmp_le_f32_e32 vcc, v250, v185
	s_mov_b64 s[52:53], vcc
	s_and_saveexec_b64 s[4:5], s[50:51]
	v_mov_b32_e32 v246, vcc_hi
	v_mov_b32_e32 v247, vcc_lo
	v_cndmask_b32_e64 v246, v246, v247, s[48:49]
	ds_write_b32 v162, v246 offset:12
	s_or_b64 exec, exec, s[4:5]
	v_cmp_le_f32_e32 vcc, v156, v185
	s_andn2_b64 vcc, vcc, s[52:53]
	s_cbranch_vccz .Lp2_skip23
	v_mov_b32_e32 v246, vcc_hi
	v_mov_b32_e32 v247, vcc_lo
	v_cndmask_b32_e64 v246, v246, v247, s[48:49]
	s_and_saveexec_b64 s[4:5], vcc
	s_cbranch_execz .Lp2_join23
	v_and_b32_e32 v247, v246, v127
	v_bcnt_u32_b32 v247, v247, v119
	v_cmp_gt_u32_e32 vcc, s35, v247
	s_and_b64 exec, exec, vcc
	s_cbranch_execz .Lp2_join23
	v_cmp_gt_f32_e64 s[52:53], 0, v185
	v_not_b32_e32 v248, v185
	s_nop 0
	v_cndmask_b32_e64 v33, -|v185|, v248, s[52:53]
	v_lshl_add_u64 v[154:155], v[94:95], 0, s[0:1]
	v_lshl_add_u64 v[154:155], v[154:155], 0, v[32:33]
	v_lshl_add_u32 v248, v247, 3, v160
	ds_write_b64 v248, v[154:155] offset:2048

.Lp2_drain2:
	v_max_i32_e32 v246, 0, v24
	v_max_i32_e32 v247, 0, v16
	v_max_i32_e32 v248, 0, v25
	v_max_i32_e32 v249, 0, v17
	v_mul_f32_e32 v184, v100, v246
	v_mul_f32_e32 v185, v101, v247
	v_fmac_f32_e32 v184, v102, v248
	v_fmac_f32_e32 v185, v103, v249
	v_max_i32_e32 v246, 0, v26
	v_max_i32_e32 v247, 0, v18
	v_max_i32_e32 v248, 0, v27
	v_max_i32_e32 v249, 0, v19
	v_fmac_f32_e32 v184, v104, v246
	v_fmac_f32_e32 v185, v105, v247
	v_fmac_f32_e32 v184, v106, v248
	v_fmac_f32_e32 v185, v107, v249
	v_max_i32_e32 v246, 0, v28
	v_max_i32_e32 v247, 0, v20
	v_max_i32_e32 v248, 0, v29
	v_max_i32_e32 v249, 0, v21
	v_fmac_f32_e32 v184, v108, v246
	v_fmac_f32_e32 v185, v109, v247
	v_fmac_f32_e32 v184, v110, v248
	v_fmac_f32_e32 v185, v111, v249
	v_max_i32_e32 v246, 0, v30
	v_max_i32_e32 v247, 0, v22
	v_max_i32_e32 v248, 0, v31
	v_max_i32_e32 v249, 0, v23
	v_fmac_f32_e32 v184, v112, v246
	v_fmac_f32_e32 v185, v113, v247
	v_fmac_f32_e32 v184, v114, v248
	v_fmac_f32_e32 v185, v115, v249
	v_cmp_le_f32_e32 vcc, v250, v185
	s_mov_b64 s[52:53], vcc
	s_and_saveexec_b64 s[4:5], s[50:51]
	v_mov_b32_e32 v246, vcc_hi
	v_mov_b32_e32 v247, vcc_lo
	v_cndmask_b32_e64 v246, v246, v247, s[48:49]
	ds_write_b32 v162, v246 offset:16
	s_or_b64 exec, exec, s[4:5]
	v_cmp_le_f32_e32 vcc, v156, v185
	s_andn2_b64 vcc, vcc, s[52:53]
	s_cbranch_vccz .Lp2_skip25
	v_mov_b32_e32 v246, vcc_hi
	v_mov_b32_e32 v247, vcc_lo
	v_cndmask_b32_e64 v246, v246, v247, s[48:49]
	s_and_saveexec_b64 s[4:5], vcc
	s_cbranch_execz .Lp2_join25
	v_and_b32_e32 v247, v246, v127
	v_bcnt_u32_b32 v247, v247, v119
	v_cmp_gt_u32_e32 vcc, s35, v247
	s_and_b64 exec, exec, vcc
	s_cbranch_execz .Lp2_join25
	v_cmp_gt_f32_e64 s[52:53], 0, v185
	v_not_b32_e32 v248, v185
	s_nop 0
	v_cndmask_b32_e64 v33, -|v185|, v248, s[52:53]
	v_lshl_add_u64 v[154:155], v[90:91], 0, s[0:1]
	v_lshl_add_u64 v[154:155], v[154:155], 0, v[32:33]
	v_lshl_add_u32 v248, v247, 3, v160
	ds_write_b64 v248, v[154:155] offset:2048

.Lp2_skip26:
	v_max_i32_e32 v246, 0, v8
	v_max_i32_e32 v247, 0, v0
	v_max_i32_e32 v248, 0, v9
	v_max_i32_e32 v249, 0, v1
	v_mul_f32_e32 v184, v100, v246
	v_mul_f32_e32 v185, v101, v247
	v_fmac_f32_e32 v184, v102, v248
	v_fmac_f32_e32 v185, v103, v249
	v_max_i32_e32 v246, 0, v10
	v_max_i32_e32 v247, 0, v2
	v_max_i32_e32 v248, 0, v11
	v_max_i32_e32 v249, 0, v3
	v_fmac_f32_e32 v184, v104, v246
	v_fmac_f32_e32 v185, v105, v247
	v_fmac_f32_e32 v184, v106, v248
	v_fmac_f32_e32 v185, v107, v249
	v_max_i32_e32 v246, 0, v12
	v_max_i32_e32 v247, 0, v4
	v_max_i32_e32 v248, 0, v13
	v_max_i32_e32 v249, 0, v5
	v_fmac_f32_e32 v184, v108, v246
	v_fmac_f32_e32 v185, v109, v247
	v_fmac_f32_e32 v184, v110, v248
	v_fmac_f32_e32 v185, v111, v249
	v_max_i32_e32 v246, 0, v14
	v_max_i32_e32 v247, 0, v6
	v_max_i32_e32 v248, 0, v15
	v_max_i32_e32 v249, 0, v7
	v_fmac_f32_e32 v184, v112, v246
	v_fmac_f32_e32 v185, v113, v247
	v_fmac_f32_e32 v184, v114, v248
	v_fmac_f32_e32 v185, v115, v249
	v_cmp_le_f32_e32 vcc, v250, v185
	s_mov_b64 s[52:53], vcc
	s_and_saveexec_b64 s[4:5], s[50:51]
	v_mov_b32_e32 v246, vcc_hi
	v_mov_b32_e32 v247, vcc_lo
	v_cndmask_b32_e64 v246, v246, v247, s[48:49]
	ds_write_b32 v162, v246 offset:20
	s_or_b64 exec, exec, s[4:5]
	v_cmp_le_f32_e32 vcc, v156, v185
	s_andn2_b64 vcc, vcc, s[52:53]
	s_cbranch_vccz .Lp2_skip27
	v_mov_b32_e32 v246, vcc_hi
	v_mov_b32_e32 v247, vcc_lo
	v_cndmask_b32_e64 v246, v246, v247, s[48:49]
	s_and_saveexec_b64 s[4:5], vcc
	s_cbranch_execz .Lp2_join27
	v_and_b32_e32 v247, v246, v127
	v_bcnt_u32_b32 v247, v247, v119
	v_cmp_gt_u32_e32 vcc, s35, v247
	s_and_b64 exec, exec, vcc
	s_cbranch_execz .Lp2_join27
	v_cmp_gt_f32_e64 s[52:53], 0, v185
	v_not_b32_e32 v248, v185
	s_nop 0
	v_cndmask_b32_e64 v33, -|v185|, v248, s[52:53]
	v_lshl_add_u64 v[154:155], v[88:89], 0, s[0:1]
	v_lshl_add_u64 v[154:155], v[154:155], 0, v[32:33]
	v_lshl_add_u32 v248, v247, 3, v160
	ds_write_b64 v248, v[154:155] offset:2048

.Lp2_drain3:
	v_max_i32_e32 v246, 0, v206
	v_max_i32_e32 v247, 0, v198
	v_max_i32_e32 v248, 0, v207
	v_max_i32_e32 v249, 0, v199
	v_mul_f32_e32 v184, v100, v246
	v_mul_f32_e32 v185, v101, v247
	v_fmac_f32_e32 v184, v102, v248
	v_fmac_f32_e32 v185, v103, v249
	v_max_i32_e32 v246, 0, v208
	v_max_i32_e32 v247, 0, v200
	v_max_i32_e32 v248, 0, v209
	v_max_i32_e32 v249, 0, v201
	v_fmac_f32_e32 v184, v104, v246
	v_fmac_f32_e32 v185, v105, v247
	v_fmac_f32_e32 v184, v106, v248
	v_fmac_f32_e32 v185, v107, v249
	v_max_i32_e32 v246, 0, v210
	v_max_i32_e32 v247, 0, v202
	v_max_i32_e32 v248, 0, v211
	v_max_i32_e32 v249, 0, v203
	v_fmac_f32_e32 v184, v108, v246
	v_fmac_f32_e32 v185, v109, v247
	v_fmac_f32_e32 v184, v110, v248
	v_fmac_f32_e32 v185, v111, v249
	v_max_i32_e32 v246, 0, v212
	v_max_i32_e32 v247, 0, v204
	v_max_i32_e32 v248, 0, v213
	v_max_i32_e32 v249, 0, v205
	v_fmac_f32_e32 v184, v112, v246
	v_fmac_f32_e32 v185, v113, v247
	v_fmac_f32_e32 v184, v114, v248
	v_fmac_f32_e32 v185, v115, v249
	v_cmp_le_f32_e32 vcc, v250, v185
	s_mov_b64 s[52:53], vcc
	s_and_saveexec_b64 s[4:5], s[50:51]
	v_mov_b32_e32 v246, vcc_hi
	v_mov_b32_e32 v247, vcc_lo
	v_cndmask_b32_e64 v246, v246, v247, s[48:49]
	ds_write_b32 v162, v246 offset:24
	s_or_b64 exec, exec, s[4:5]
	v_cmp_le_f32_e32 vcc, v156, v185
	s_andn2_b64 vcc, vcc, s[52:53]
	s_cbranch_vccz .Lp2_skip29
	v_mov_b32_e32 v246, vcc_hi
	v_mov_b32_e32 v247, vcc_lo
	v_cndmask_b32_e64 v246, v246, v247, s[48:49]
	s_and_saveexec_b64 s[4:5], vcc
	s_cbranch_execz .Lp2_join29
	v_and_b32_e32 v247, v246, v127
	v_bcnt_u32_b32 v247, v247, v119
	v_cmp_gt_u32_e32 vcc, s35, v247
	s_and_b64 exec, exec, vcc
	s_cbranch_execz .Lp2_join29
	v_cmp_gt_f32_e64 s[52:53], 0, v185
	v_not_b32_e32 v248, v185
	s_nop 0
	v_cndmask_b32_e64 v33, -|v185|, v248, s[52:53]
	v_lshl_add_u64 v[154:155], v[86:87], 0, s[0:1]
	v_lshl_add_u64 v[154:155], v[154:155], 0, v[32:33]
	v_lshl_add_u32 v248, v247, 3, v160
	ds_write_b64 v248, v[154:155] offset:2048

.Lp2_skip30:
	v_max_i32_e32 v246, 0, v222
	v_max_i32_e32 v247, 0, v214
	v_max_i32_e32 v248, 0, v223
	v_max_i32_e32 v249, 0, v215
	v_mul_f32_e32 v184, v100, v246
	v_mul_f32_e32 v185, v101, v247
	v_fmac_f32_e32 v184, v102, v248
	v_fmac_f32_e32 v185, v103, v249
	v_max_i32_e32 v246, 0, v224
	v_max_i32_e32 v247, 0, v216
	v_max_i32_e32 v248, 0, v225
	v_max_i32_e32 v249, 0, v217
	v_fmac_f32_e32 v184, v104, v246
	v_fmac_f32_e32 v185, v105, v247
	v_fmac_f32_e32 v184, v106, v248
	v_fmac_f32_e32 v185, v107, v249
	v_max_i32_e32 v246, 0, v226
	v_max_i32_e32 v247, 0, v218
	v_max_i32_e32 v248, 0, v227
	v_max_i32_e32 v249, 0, v219
	v_fmac_f32_e32 v184, v108, v246
	v_fmac_f32_e32 v185, v109, v247
	v_fmac_f32_e32 v184, v110, v248
	v_fmac_f32_e32 v185, v111, v249
	v_max_i32_e32 v246, 0, v228
	v_max_i32_e32 v247, 0, v220
	v_max_i32_e32 v248, 0, v229
	v_max_i32_e32 v249, 0, v221
	v_fmac_f32_e32 v184, v112, v246
	v_fmac_f32_e32 v185, v113, v247
	v_fmac_f32_e32 v184, v114, v248
	v_fmac_f32_e32 v185, v115, v249
	v_cmp_le_f32_e32 vcc, v250, v185
	s_mov_b64 s[52:53], vcc
	s_and_saveexec_b64 s[4:5], s[50:51]
	v_mov_b32_e32 v246, vcc_hi
	v_mov_b32_e32 v247, vcc_lo
	v_cndmask_b32_e64 v246, v246, v247, s[48:49]
	ds_write_b32 v162, v246 offset:28
	s_or_b64 exec, exec, s[4:5]
	v_cmp_le_f32_e32 vcc, v156, v185
	s_andn2_b64 vcc, vcc, s[52:53]
	s_cbranch_vccz .Lp2_skip31
	v_mov_b32_e32 v246, vcc_hi
	v_mov_b32_e32 v247, vcc_lo
	v_cndmask_b32_e64 v246, v246, v247, s[48:49]
	s_and_saveexec_b64 s[4:5], vcc
	s_cbranch_execz .Lp2_join31
	v_and_b32_e32 v247, v246, v127
	v_bcnt_u32_b32 v247, v247, v119
	v_cmp_gt_u32_e32 vcc, s35, v247
	s_and_b64 exec, exec, vcc
	s_cbranch_execz .Lp2_join31
	v_cmp_gt_f32_e64 s[52:53], 0, v185
	v_not_b32_e32 v248, v185
	s_nop 0
	v_cndmask_b32_e64 v33, -|v185|, v248, s[52:53]
	v_lshl_add_u64 v[154:155], v[84:85], 0, s[0:1]
	v_lshl_add_u64 v[154:155], v[154:155], 0, v[32:33]
	v_lshl_add_u32 v248, v247, 3, v160
	ds_write_b64 v248, v[154:155] offset:2048
